# v83 + adaLN w_ada loop refill-pipelined (16 loads always in flight, saddr addressing)
# baseline (speedup 1.0000x reference)
; __global__ void __launch_bounds__(NTHR, 2) fwd_kernel(Args a) {
;     ...
;         for (int cb = bx; cb < 256; cb += G) {
;             const int col = cb * 48 + (lane < 48 ? lane : 47);
;             float acc[5] = {0.f, 0.f, 0.f, 0.f, 0.f};
;             const float* wp = a.in[I_WADA] + (size_t)(wave * 256) * MODW + col;
; #pragma unroll 16
;             for (int kk = 0; kk < 256; ++kk) {
;                 const float w = wp[(size_t)kk * MODW];
; #pragma unroll
;                 for (int r = 0; r < 5; ++r) acc[r] += w * sl[r * DM + wave * 256 + kk];
;             }
.LBB0_103:
	v_ashrrev_i32_e32 v3, 31, v2
	v_lshl_add_u64 v[4:5], v[2:3], 2, s[0:1]
	v_mov_b32_e32 v3, 0
	s_mov_b64 s[12:13], 0
	s_mov_b32 s33, s15
	v_mov_b32_e32 v6, 0
	v_mov_b32_e32 v7, v3
	v_mov_b32_e32 v8, 0
	v_mov_b32_e32 v9, v3
	v_lshlrev_b32_e32 v95, 2, v2
	v_add_u32_e32 v97, s14, v95
	v_add_u32_e32 v99, s17, v95
	v_add_u32_e32 v101, s18, v95
	v_add_u32_e32 v103, s19, v95
	v_add_u32_e32 v105, s20, v95
	v_add_u32_e32 v107, s21, v95
	v_add_u32_e32 v109, s22, v95
	v_add_u32_e32 v111, s23, v95
	v_add_u32_e32 v113, s24, v95
	v_add_u32_e32 v115, s25, v95
	v_add_u32_e32 v117, s26, v95
	v_add_u32_e32 v119, s27, v95
	v_add_u32_e32 v121, s28, v95
	v_add_u32_e32 v123, s29, v95
	v_add_u32_e32 v11, s30, v95
	global_load_dword v94, v95, s[0:1] nt
	global_load_dword v96, v97, s[0:1] nt
	global_load_dword v98, v99, s[0:1] nt
	global_load_dword v100, v101, s[0:1] nt
	global_load_dword v102, v103, s[0:1] nt
	global_load_dword v104, v105, s[0:1] nt
	global_load_dword v106, v107, s[0:1] nt
	global_load_dword v108, v109, s[0:1] nt
	global_load_dword v110, v111, s[0:1] nt
	global_load_dword v112, v113, s[0:1] nt
	global_load_dword v114, v115, s[0:1] nt
	global_load_dword v116, v117, s[0:1] nt
	global_load_dword v118, v119, s[0:1] nt
	global_load_dword v120, v121, s[0:1] nt
	global_load_dword v122, v123, s[0:1] nt
	global_load_dword v10, v11, s[0:1] nt
.LBB0_104:
	s_nop 0
	v_mov_b32_e32 v90, s33
	s_nop 0
	ds_read_b128 v[14:17], v90
	ds_read_b128 v[18:21], v90 offset:16
	ds_read_b128 v[22:25], v90 offset:8192
	ds_read_b128 v[26:29], v90 offset:8208
	ds_read_b128 v[30:33], v90 offset:16384
	ds_read_b128 v[34:37], v90 offset:16400
	ds_read_b128 v[38:41], v90 offset:24576
	ds_read_b128 v[42:45], v90 offset:24592
	ds_read_b128 v[46:49], v90 offset:32768
	ds_read_b128 v[50:53], v90 offset:32784
	ds_read_b128 v[54:57], v90 offset:32
	ds_read_b128 v[58:61], v90 offset:48
	ds_read_b128 v[62:65], v90 offset:8224
	ds_read_b128 v[66:69], v90 offset:8240
	ds_read_b128 v[70:73], v90 offset:16416
	ds_read_b128 v[74:77], v90 offset:16432
	ds_read_b128 v[78:81], v90 offset:24608
	ds_read_b128 v[82:85], v90 offset:24624
	ds_read_b128 v[86:89], v90 offset:32800
	ds_read_b128 v[90:93], v90 offset:32816
	s_waitcnt lgkmcnt(14)
	v_mov_b32_e32 v124, v30
	v_mov_b32_e32 v125, v22
	s_nop 0
	v_mov_b32_e32 v22, v31
	s_nop 0
	v_mov_b32_e32 v30, v32
	s_nop 0
	v_mov_b32_e32 v31, v24
	s_nop 0
	v_mov_b32_e32 v24, v33
	s_nop 0
	s_waitcnt lgkmcnt(11)
	v_mov_b32_e32 v32, v46
	v_mov_b32_e32 v33, v38
	s_nop 0
	v_mov_b32_e32 v38, v47
	s_nop 0
	s_nop 0
	s_nop 0
	s_nop 0
	s_nop 0
	s_nop 0
	s_nop 0
	s_nop 0
	s_nop 0
	s_nop 0
	s_nop 0
	s_nop 0
	s_nop 0
	s_nop 0
	s_nop 0
	v_mov_b32_e32 v46, v48
	v_mov_b32_e32 v47, v40
	v_mov_b32_e32 v40, v49
	v_mov_b32_e32 v48, v34
	v_mov_b32_e32 v49, v26
	v_mov_b32_e32 v26, v35
	s_waitcnt vmcnt(15)
	v_pk_fma_f32 v[8:9], v[94:95], v[124:125], v[8:9] op_sel_hi:[0,1,1]
	v_pk_fma_f32 v[6:7], v[94:95], v[32:33], v[6:7] op_sel_hi:[0,1,1]
	v_fmac_f32_e32 v3, v94, v14
	v_mov_b32_e32 v34, v36
	v_mov_b32_e32 v35, v28
	v_mov_b32_e32 v28, v37
	s_waitcnt lgkmcnt(10)
	v_mov_b32_e32 v36, v50
	v_mov_b32_e32 v37, v42
	v_mov_b32_e32 v42, v51
	v_mov_b32_e32 v50, v52
	v_mov_b32_e32 v51, v44
	v_mov_b32_e32 v44, v53
	s_waitcnt lgkmcnt(5)
	v_mov_b32_e32 v52, v70
	v_mov_b32_e32 v53, v62
	v_mov_b32_e32 v62, v71
	v_mov_b32_e32 v70, v72
	v_mov_b32_e32 v71, v64
	v_mov_b32_e32 v64, v73
	s_waitcnt lgkmcnt(1)
	v_mov_b32_e32 v72, v86
	v_mov_b32_e32 v73, v78
	v_mov_b32_e32 v78, v87
	v_mov_b32_e32 v86, v88
	v_mov_b32_e32 v87, v80
	v_mov_b32_e32 v80, v89
	v_mov_b32_e32 v88, v74
	v_mov_b32_e32 v89, v66
	v_mov_b32_e32 v66, v75
	v_mov_b32_e32 v74, v76
	v_mov_b32_e32 v75, v68
	v_mov_b32_e32 v68, v77
	s_waitcnt lgkmcnt(0)
	v_mov_b32_e32 v76, v90
	v_mov_b32_e32 v77, v82
	v_mov_b32_e32 v82, v91
	s_add_u32 s12, s12, 0xc0000
	v_mov_b32_e32 v90, v92
	v_mov_b32_e32 v91, v84
	s_addc_u32 s13, s13, 0
	s_add_i32 s33, s33, 64
	v_mov_b32_e32 v84, v93
	s_cmp_eq_u32 s12, 0xb40000
	v_add_u32_e32 v95, 0xc0000, v95
	global_load_dword v94, v95, s[0:1] nt
	s_waitcnt vmcnt(15)
	v_fmac_f32_e32 v3, v96, v15
	v_pk_fma_f32 v[8:9], v[96:97], v[22:23], v[8:9] op_sel_hi:[0,1,1]
	v_pk_fma_f32 v[6:7], v[96:97], v[38:39], v[6:7] op_sel_hi:[0,1,1]
	v_add_u32_e32 v97, 0xc0000, v97
	global_load_dword v96, v97, s[0:1] nt
	s_waitcnt vmcnt(15)
	v_pk_fma_f32 v[8:9], v[98:99], v[30:31], v[8:9] op_sel_hi:[0,1,1]
	v_pk_fma_f32 v[6:7], v[98:99], v[46:47], v[6:7] op_sel_hi:[0,1,1]
	v_fmac_f32_e32 v3, v98, v16
	v_add_u32_e32 v99, 0xc0000, v99
	global_load_dword v98, v99, s[0:1] nt
	s_waitcnt vmcnt(15)
	v_fmac_f32_e32 v3, v100, v17
	v_pk_fma_f32 v[8:9], v[100:101], v[24:25], v[8:9] op_sel_hi:[0,1,1]
	v_pk_fma_f32 v[6:7], v[100:101], v[40:41], v[6:7] op_sel_hi:[0,1,1]
	v_add_u32_e32 v101, 0xc0000, v101
	global_load_dword v100, v101, s[0:1] nt
	s_waitcnt vmcnt(15)
	v_pk_fma_f32 v[8:9], v[102:103], v[48:49], v[8:9] op_sel_hi:[0,1,1]
	v_pk_fma_f32 v[6:7], v[102:103], v[36:37], v[6:7] op_sel_hi:[0,1,1]
	v_fmac_f32_e32 v3, v102, v18
	v_add_u32_e32 v103, 0xc0000, v103
	global_load_dword v102, v103, s[0:1] nt
	s_waitcnt vmcnt(15)
	v_fmac_f32_e32 v3, v104, v19
	v_pk_fma_f32 v[8:9], v[104:105], v[26:27], v[8:9] op_sel_hi:[0,1,1]
	v_pk_fma_f32 v[6:7], v[104:105], v[42:43], v[6:7] op_sel_hi:[0,1,1]
	v_add_u32_e32 v105, 0xc0000, v105
	global_load_dword v104, v105, s[0:1] nt
	s_waitcnt vmcnt(15)
	v_pk_fma_f32 v[8:9], v[106:107], v[34:35], v[8:9] op_sel_hi:[0,1,1]
	v_pk_fma_f32 v[6:7], v[106:107], v[50:51], v[6:7] op_sel_hi:[0,1,1]
	v_fmac_f32_e32 v3, v106, v20
	v_add_u32_e32 v107, 0xc0000, v107
	global_load_dword v106, v107, s[0:1] nt
	s_waitcnt vmcnt(15)
; __global__ void __launch_bounds__(NTHR, 2) fwd_kernel(Args a) {
;     ...
;             for (int kk = 0; kk < 256; ++kk) {
;                 const float w = wp[(size_t)kk * MODW];
; #pragma unroll
;                 for (int r = 0; r < 5; ++r) acc[r] += w * sl[r * DM + wave * 256 + kk];
;             }
	v_fmac_f32_e32 v3, v108, v21
	v_pk_fma_f32 v[8:9], v[108:109], v[28:29], v[8:9] op_sel_hi:[0,1,1]
	v_pk_fma_f32 v[6:7], v[108:109], v[44:45], v[6:7] op_sel_hi:[0,1,1]
	v_add_u32_e32 v109, 0xc0000, v109
	global_load_dword v108, v109, s[0:1] nt
	s_waitcnt vmcnt(15)
	v_fmac_f32_e32 v3, v110, v54
	v_pk_fma_f32 v[8:9], v[110:111], v[52:53], v[8:9] op_sel_hi:[0,1,1]
	v_pk_fma_f32 v[6:7], v[110:111], v[72:73], v[6:7] op_sel_hi:[0,1,1]
	v_add_u32_e32 v111, 0xc0000, v111
	global_load_dword v110, v111, s[0:1] nt
	s_waitcnt vmcnt(15)
	v_fmac_f32_e32 v3, v112, v55
	v_pk_fma_f32 v[8:9], v[112:113], v[62:63], v[8:9] op_sel_hi:[0,1,1]
	v_pk_fma_f32 v[6:7], v[112:113], v[78:79], v[6:7] op_sel_hi:[0,1,1]
	v_add_u32_e32 v113, 0xc0000, v113
	global_load_dword v112, v113, s[0:1] nt
	s_waitcnt vmcnt(15)
	v_fmac_f32_e32 v3, v114, v56
	v_pk_fma_f32 v[8:9], v[114:115], v[70:71], v[8:9] op_sel_hi:[0,1,1]
	v_pk_fma_f32 v[6:7], v[114:115], v[86:87], v[6:7] op_sel_hi:[0,1,1]
	v_add_u32_e32 v115, 0xc0000, v115
	global_load_dword v114, v115, s[0:1] nt
	s_waitcnt vmcnt(15)
	v_fmac_f32_e32 v3, v116, v57
	v_pk_fma_f32 v[8:9], v[116:117], v[64:65], v[8:9] op_sel_hi:[0,1,1]
	v_pk_fma_f32 v[6:7], v[116:117], v[80:81], v[6:7] op_sel_hi:[0,1,1]
	v_add_u32_e32 v117, 0xc0000, v117
	global_load_dword v116, v117, s[0:1] nt
	s_waitcnt vmcnt(15)
	v_fmac_f32_e32 v3, v118, v58
	v_pk_fma_f32 v[8:9], v[118:119], v[88:89], v[8:9] op_sel_hi:[0,1,1]
	v_pk_fma_f32 v[6:7], v[118:119], v[76:77], v[6:7] op_sel_hi:[0,1,1]
	v_add_u32_e32 v119, 0xc0000, v119
	global_load_dword v118, v119, s[0:1] nt
	s_waitcnt vmcnt(15)
	v_fmac_f32_e32 v3, v120, v59
	v_pk_fma_f32 v[8:9], v[120:121], v[66:67], v[8:9] op_sel_hi:[0,1,1]
	v_pk_fma_f32 v[6:7], v[120:121], v[82:83], v[6:7] op_sel_hi:[0,1,1]
	v_add_u32_e32 v121, 0xc0000, v121
	global_load_dword v120, v121, s[0:1] nt
	s_waitcnt vmcnt(15)
	v_fmac_f32_e32 v3, v122, v60
	v_pk_fma_f32 v[8:9], v[122:123], v[74:75], v[8:9] op_sel_hi:[0,1,1]
	v_pk_fma_f32 v[6:7], v[122:123], v[90:91], v[6:7] op_sel_hi:[0,1,1]
	v_add_u32_e32 v123, 0xc0000, v123
	global_load_dword v122, v123, s[0:1] nt
	s_waitcnt vmcnt(15)
	v_fmac_f32_e32 v3, v10, v61
	v_pk_fma_f32 v[8:9], v[10:11], v[68:69], v[8:9] op_sel_hi:[0,1,1]
	v_pk_fma_f32 v[6:7], v[10:11], v[84:85], v[6:7] op_sel_hi:[0,1,1]
	v_add_u32_e32 v11, 0xc0000, v11
	global_load_dword v10, v11, s[0:1] nt
	s_cbranch_scc0 .LBB0_104
; __global__ void __launch_bounds__(NTHR, 2) fwd_kernel(Args a) {
;     ...
;             for (int kk = 0; kk < 256; ++kk) {
;                 const float w = wp[(size_t)kk * MODW];
; #pragma unroll
;                 for (int r = 0; r < 5; ++r) acc[r] += w * sl[r * DM + wave * 256 + kk];
;             }
;             if (lane < 48) {
; #pragma unroll
;                 for (int r = 0; r < 5; ++r) red[(wave * 5 + r) * 48 + lane] = acc[r];
;             }
	s_nop 0
	v_mov_b32_e32 v90, s33
	s_nop 0
	ds_read_b128 v[14:17], v90
	ds_read_b128 v[18:21], v90 offset:16
	ds_read_b128 v[22:25], v90 offset:8192
	ds_read_b128 v[26:29], v90 offset:8208
	ds_read_b128 v[30:33], v90 offset:16384
	ds_read_b128 v[34:37], v90 offset:16400
	ds_read_b128 v[38:41], v90 offset:24576
	ds_read_b128 v[42:45], v90 offset:24592
	ds_read_b128 v[46:49], v90 offset:32768
	ds_read_b128 v[50:53], v90 offset:32784
	ds_read_b128 v[54:57], v90 offset:32
	ds_read_b128 v[58:61], v90 offset:48
	ds_read_b128 v[62:65], v90 offset:8224
	ds_read_b128 v[66:69], v90 offset:8240
	ds_read_b128 v[70:73], v90 offset:16416
	ds_read_b128 v[74:77], v90 offset:16432
	ds_read_b128 v[78:81], v90 offset:24608
	ds_read_b128 v[82:85], v90 offset:24624
	ds_read_b128 v[86:89], v90 offset:32800
	ds_read_b128 v[90:93], v90 offset:32816
	s_waitcnt lgkmcnt(14)
	v_mov_b32_e32 v124, v30
	v_mov_b32_e32 v125, v22
	s_nop 0
	v_mov_b32_e32 v22, v31
	s_nop 0
	v_mov_b32_e32 v30, v32
	s_nop 0
	v_mov_b32_e32 v31, v24
	s_nop 0
	v_mov_b32_e32 v24, v33
	s_nop 0
	s_waitcnt lgkmcnt(11)
	v_mov_b32_e32 v32, v46
	v_mov_b32_e32 v33, v38
	s_nop 0
	v_mov_b32_e32 v38, v47
	s_nop 0
	s_nop 0
	s_nop 0
	s_nop 0
	s_nop 0
	s_nop 0
	s_nop 0
	s_nop 0
	s_nop 0
	s_nop 0
	s_nop 0
	s_nop 0
	s_nop 0
	s_nop 0
	s_nop 0
	v_mov_b32_e32 v46, v48
	v_mov_b32_e32 v47, v40
	v_mov_b32_e32 v40, v49
	v_mov_b32_e32 v48, v34
	v_mov_b32_e32 v49, v26
	v_mov_b32_e32 v26, v35
	s_waitcnt vmcnt(15)
	v_pk_fma_f32 v[8:9], v[94:95], v[124:125], v[8:9] op_sel_hi:[0,1,1]
	v_pk_fma_f32 v[6:7], v[94:95], v[32:33], v[6:7] op_sel_hi:[0,1,1]
	v_fmac_f32_e32 v3, v94, v14
	v_mov_b32_e32 v34, v36
	v_mov_b32_e32 v35, v28
	v_mov_b32_e32 v28, v37
	s_waitcnt lgkmcnt(10)
	v_mov_b32_e32 v36, v50
	v_mov_b32_e32 v37, v42
	v_mov_b32_e32 v42, v51
	v_mov_b32_e32 v50, v52
	v_mov_b32_e32 v51, v44
	v_mov_b32_e32 v44, v53
	s_waitcnt lgkmcnt(5)
	v_mov_b32_e32 v52, v70
	v_mov_b32_e32 v53, v62
	v_mov_b32_e32 v62, v71
	v_mov_b32_e32 v70, v72
	v_mov_b32_e32 v71, v64
	v_mov_b32_e32 v64, v73
	s_waitcnt lgkmcnt(1)
	v_mov_b32_e32 v72, v86
	v_mov_b32_e32 v73, v78
	v_mov_b32_e32 v78, v87
	v_mov_b32_e32 v86, v88
	v_mov_b32_e32 v87, v80
	v_mov_b32_e32 v80, v89
	v_mov_b32_e32 v88, v74
	v_mov_b32_e32 v89, v66
	v_mov_b32_e32 v66, v75
	v_mov_b32_e32 v74, v76
	v_mov_b32_e32 v75, v68
	v_mov_b32_e32 v68, v77
	s_waitcnt lgkmcnt(0)
	v_mov_b32_e32 v76, v90
	v_mov_b32_e32 v77, v82
	v_mov_b32_e32 v82, v91
	s_add_u32 s12, s12, 0xc0000
	v_mov_b32_e32 v90, v92
	v_mov_b32_e32 v91, v84
	s_addc_u32 s13, s13, 0
	s_add_i32 s33, s33, 64
	v_mov_b32_e32 v84, v93
	s_cmp_eq_u32 s12, 0xc00000
	s_waitcnt vmcnt(14)
	v_fmac_f32_e32 v3, v96, v15
	v_pk_fma_f32 v[8:9], v[96:97], v[22:23], v[8:9] op_sel_hi:[0,1,1]
	v_pk_fma_f32 v[6:7], v[96:97], v[38:39], v[6:7] op_sel_hi:[0,1,1]
	s_waitcnt vmcnt(13)
	v_pk_fma_f32 v[8:9], v[98:99], v[30:31], v[8:9] op_sel_hi:[0,1,1]
	v_pk_fma_f32 v[6:7], v[98:99], v[46:47], v[6:7] op_sel_hi:[0,1,1]
	v_fmac_f32_e32 v3, v98, v16
	s_waitcnt vmcnt(12)
	v_fmac_f32_e32 v3, v100, v17
	v_pk_fma_f32 v[8:9], v[100:101], v[24:25], v[8:9] op_sel_hi:[0,1,1]
	v_pk_fma_f32 v[6:7], v[100:101], v[40:41], v[6:7] op_sel_hi:[0,1,1]
	s_waitcnt vmcnt(11)
	v_pk_fma_f32 v[8:9], v[102:103], v[48:49], v[8:9] op_sel_hi:[0,1,1]
	v_pk_fma_f32 v[6:7], v[102:103], v[36:37], v[6:7] op_sel_hi:[0,1,1]
	v_fmac_f32_e32 v3, v102, v18
	s_waitcnt vmcnt(10)
	v_fmac_f32_e32 v3, v104, v19
	v_pk_fma_f32 v[8:9], v[104:105], v[26:27], v[8:9] op_sel_hi:[0,1,1]
	v_pk_fma_f32 v[6:7], v[104:105], v[42:43], v[6:7] op_sel_hi:[0,1,1]
	s_waitcnt vmcnt(9)
	v_pk_fma_f32 v[8:9], v[106:107], v[34:35], v[8:9] op_sel_hi:[0,1,1]
	v_pk_fma_f32 v[6:7], v[106:107], v[50:51], v[6:7] op_sel_hi:[0,1,1]
	v_fmac_f32_e32 v3, v106, v20
	s_waitcnt vmcnt(8)
	v_fmac_f32_e32 v3, v108, v21
	v_pk_fma_f32 v[8:9], v[108:109], v[28:29], v[8:9] op_sel_hi:[0,1,1]
	v_pk_fma_f32 v[6:7], v[108:109], v[44:45], v[6:7] op_sel_hi:[0,1,1]
	s_waitcnt vmcnt(7)
	v_fmac_f32_e32 v3, v110, v54
	v_pk_fma_f32 v[8:9], v[110:111], v[52:53], v[8:9] op_sel_hi:[0,1,1]
	v_pk_fma_f32 v[6:7], v[110:111], v[72:73], v[6:7] op_sel_hi:[0,1,1]
	s_waitcnt vmcnt(6)
	v_fmac_f32_e32 v3, v112, v55
	v_pk_fma_f32 v[8:9], v[112:113], v[62:63], v[8:9] op_sel_hi:[0,1,1]
	v_pk_fma_f32 v[6:7], v[112:113], v[78:79], v[6:7] op_sel_hi:[0,1,1]
	s_waitcnt vmcnt(5)
	v_fmac_f32_e32 v3, v114, v56
	v_pk_fma_f32 v[8:9], v[114:115], v[70:71], v[8:9] op_sel_hi:[0,1,1]
	v_pk_fma_f32 v[6:7], v[114:115], v[86:87], v[6:7] op_sel_hi:[0,1,1]
	s_waitcnt vmcnt(4)
	v_fmac_f32_e32 v3, v116, v57
	v_pk_fma_f32 v[8:9], v[116:117], v[64:65], v[8:9] op_sel_hi:[0,1,1]
	v_pk_fma_f32 v[6:7], v[116:117], v[80:81], v[6:7] op_sel_hi:[0,1,1]
	s_waitcnt vmcnt(3)
	v_fmac_f32_e32 v3, v118, v58
	v_pk_fma_f32 v[8:9], v[118:119], v[88:89], v[8:9] op_sel_hi:[0,1,1]
	v_pk_fma_f32 v[6:7], v[118:119], v[76:77], v[6:7] op_sel_hi:[0,1,1]
	s_waitcnt vmcnt(2)
	v_fmac_f32_e32 v3, v120, v59
	v_pk_fma_f32 v[8:9], v[120:121], v[66:67], v[8:9] op_sel_hi:[0,1,1]
	v_pk_fma_f32 v[6:7], v[120:121], v[82:83], v[6:7] op_sel_hi:[0,1,1]
	s_waitcnt vmcnt(1)
	v_fmac_f32_e32 v3, v122, v60
	v_pk_fma_f32 v[8:9], v[122:123], v[74:75], v[8:9] op_sel_hi:[0,1,1]
	v_pk_fma_f32 v[6:7], v[122:123], v[90:91], v[6:7] op_sel_hi:[0,1,1]
	s_waitcnt vmcnt(0)
	v_fmac_f32_e32 v3, v10, v61
	v_pk_fma_f32 v[8:9], v[10:11], v[68:69], v[8:9] op_sel_hi:[0,1,1]
	v_pk_fma_f32 v[6:7], v[10:11], v[84:85], v[6:7] op_sel_hi:[0,1,1]
	s_and_saveexec_b64 s[4:5], vcc
	s_cbranch_execz .LBB0_107
	v_add_u32_e32 v4, 0xa000, v12
	ds_write2_b32 v4, v3, v9 offset1:48
	ds_write2_b32 v4, v8, v7 offset0:96 offset1:144
	ds_write_b32 v12, v6 offset:41728
